# gemm_phase prologues (10 calls): K-tile 1's six LDS-DMA loads issued together with K-tile 0's eight, one cold latency instead of two (vmcnt 2->8)
# speedup vs baseline: 1.0041x; 1.0041x over previous
; #define PG8_STAGE(bufoff, gbase, voff) do { _Pragma("unroll") for (int _i = 0; _i < 2; ++_i) \
;         __builtin_amdgcn_global_load_lds((const unsigned*)((const char*)(gbase) + (voff)[_i]), (PG8_LAS unsigned*)(lds + (bufoff) + ldsw + _i * 8192), 16, 0, 0); } while (0)
; #define PG8_WAIT_V(n) asm volatile("s_waitcnt vmcnt(" #n ")" ::: "memory")
; #define PG8_BAR __builtin_amdgcn_s_barrier()
; template <class Epi, class Sched, bool ALIGN_EPI = false, bool SP2 = false>
; __device__ __forceinline__ void gemm_phase(PG8_LAS unsigned char* lds, const Gemm g, const Sched& S, const Epi& E) {
;     ...
;         PG8_STAGE(PG8_SB(0, 0), cB, voffB); PG8_STAGE(PG8_SB(0, 1), cB + hstep, voffB); PG8_STAGE(PG8_SA(0, 0), cA, voffA); PG8_STAGE(PG8_SA(0, 1), cA + hstep, voffA);
;         if (wr == 1) PG8_BAR;
;         PG8_WAIT_V(2); PG8_BAR;
;         PG8_STAGE(PG8_SB(1, 0), cB + kstep, voffB); PG8_STAGE(PG8_SA(1, 0), cA + kstep, voffA); PG8_STAGE(PG8_SB(1, 1), cB + hstep + kstep, voffB);
;         PG8_WAIT_V(6); PG8_BAR;
.LBB0_228:
	s_lshl_b32 s20, s20, 5
	s_and_b32 s44, s20, 0x60
	s_mov_b64 s[20:21], 0x80
	s_add_i32 m0, s57, 0x18000
	v_lshl_add_u64 v[6:7], v[6:7], 0, s[20:21]
	s_lshl_b32 s27, s26, 13
	global_load_lds_dwordx4 v[6:7], off
	v_lshl_add_u64 v[4:5], v[4:5], 0, s[20:21]
	s_add_i32 m0, s57, 0x1a000
	s_add_i32 s65, s57, 0x8000
	s_add_i32 s66, s57, 0xa000
	global_load_lds_dwordx4 v[4:5], off
	v_lshl_add_u64 v[0:1], v[0:1], 0, s[20:21]
	s_mov_b32 m0, s65
	s_add_u32 s34, s6, 0x40080
	global_load_lds_dwordx4 v[0:1], off
	v_lshl_add_u64 v[0:1], v[2:3], 0, s[20:21]
	s_mov_b32 m0, s66
	s_addc_u32 s35, s7, 0
	global_load_lds_dwordx4 v[0:1], off
	s_add_i32 m0, s57, 0x1c000
	v_lshl_add_u64 v[0:1], s[34:35], 0, v[132:133]
	global_load_lds_dwordx4 v[0:1], off
	v_lshl_add_u64 v[0:1], s[34:35], 0, v[128:129]
	s_add_i32 m0, s57, 0x1e000
	v_lshlrev_b32_e32 v2, 11, v10
	global_load_lds_dwordx4 v[0:1], off
	s_waitcnt vmcnt(8)
	s_barrier
	v_lshlrev_b32_e32 v1, 2, v149
	v_lshl_or_b32 v0, v149, 6, v150
	v_and_b32_e32 v1, 32, v1
	v_bitop3_b32 v0, v0, s27, v1 bitop3:0xde
	v_lshlrev_b32_e32 v1, 8, v221
	v_and_b32_e32 v1, 0x38000, v1
	v_or3_b32 v1, v8, v1, v2
	v_add_u32_e32 v136, v1, v9
	v_lshlrev_b32_e32 v1, 4, v11
	s_waitcnt vmcnt(6)
	s_cmpk_lt_u32 s1, 0x100
	v_and_b32_e32 v1, 0x78000, v1
	v_lshl_or_b32 v157, s26, 6, v149
	v_lshl_or_b32 v158, s44, 7, v151
	s_cselect_b64 s[26:27], -1, 0
	v_or3_b32 v1, v8, v1, v2
	s_add_i32 s77, 0, 0x10000
	s_add_i32 s78, 0, 0x14000
	s_sext_i32_i16 s80, s0
	s_ashr_i32 s67, s74, 31
	s_mov_b32 s76, s74
	v_or_b32_e32 v159, s44, v148
	v_mov_b32_e32 v137, v133
	v_add_u32_e32 v138, v1, v9
	v_mov_b32_e32 v139, v133
	v_mov_b64_e32 v[140:141], 0x600
	v_mov_b64_e32 v[142:143], 0x5ff
	v_add_u32_e32 v160, s77, v158
	v_add_u32_e32 v161, s78, v158
	v_add_u32_e32 v162, 0, v0
	s_mov_b32 s79, 0xb00000
	s_barrier
	s_branch .LBB0_231

; #define PG8_STAGE(bufoff, gbase, voff) do { _Pragma("unroll") for (int _i = 0; _i < 2; ++_i) \
;         __builtin_amdgcn_global_load_lds((const unsigned*)((const char*)(gbase) + (voff)[_i]), (PG8_LAS unsigned*)(lds + (bufoff) + ldsw + _i * 8192), 16, 0, 0); } while (0)
; #define PG8_WAIT_V(n) asm volatile("s_waitcnt vmcnt(" #n ")" ::: "memory")
; #define PG8_BAR __builtin_amdgcn_s_barrier()
; template <class Epi, class Sched, bool ALIGN_EPI = false, bool SP2 = false>
; __device__ __forceinline__ void gemm_phase(PG8_LAS unsigned char* lds, const Gemm g, const Sched& S, const Epi& E) {
;     ...
;         PG8_STAGE(PG8_SB(0, 0), cB, voffB); PG8_STAGE(PG8_SB(0, 1), cB + hstep, voffB); PG8_STAGE(PG8_SA(0, 0), cA, voffA); PG8_STAGE(PG8_SA(0, 1), cA + hstep, voffA);
;         if (wr == 1) PG8_BAR;
;         PG8_WAIT_V(2); PG8_BAR;
;         PG8_STAGE(PG8_SB(1, 0), cB + kstep, voffB); PG8_STAGE(PG8_SA(1, 0), cA + kstep, voffA); PG8_STAGE(PG8_SB(1, 1), cB + hstep + kstep, voffB);
;         PG8_WAIT_V(6); PG8_BAR;
.LBB0_248:
	s_lshl_b32 s20, s20, 5
	s_and_b32 s30, s20, 0x60
	s_mov_b64 s[20:21], 0x80
	s_add_i32 m0, s7, 0x18000
	v_lshl_add_u64 v[6:7], v[6:7], 0, s[20:21]
	s_lshl_b32 s27, s1, 13
	global_load_lds_dwordx4 v[6:7], off
	v_lshl_add_u64 v[4:5], v[4:5], 0, s[20:21]
	s_add_i32 m0, s7, 0x1a000
	s_add_i32 s78, s7, 0x8000
	s_add_i32 s79, s7, 0xa000
	global_load_lds_dwordx4 v[4:5], off
	v_lshl_add_u64 v[0:1], v[0:1], 0, s[20:21]
	s_mov_b32 m0, s78
	s_add_u32 s34, s10, 0x8080
	global_load_lds_dwordx4 v[0:1], off
	v_lshl_add_u64 v[0:1], v[2:3], 0, s[20:21]
	s_mov_b32 m0, s79
	s_addc_u32 s35, s11, 0
	global_load_lds_dwordx4 v[0:1], off
	s_add_i32 m0, s7, 0x1c000
	v_lshl_add_u64 v[0:1], s[34:35], 0, v[130:131]
	global_load_lds_dwordx4 v[0:1], off
	v_lshl_add_u64 v[0:1], s[34:35], 0, v[134:135]
	s_add_i32 m0, s7, 0x1e000
	s_cmpk_lt_u32 s26, 0x100
	global_load_lds_dwordx4 v[0:1], off
	s_waitcnt vmcnt(8)
	s_barrier
	v_lshlrev_b32_e32 v1, 2, v149
	v_lshl_or_b32 v0, v149, 6, v150
	v_and_b32_e32 v1, 32, v1
	v_bitop3_b32 v0, v0, s27, v1 bitop3:0xde
	s_cselect_b64 s[26:27], -1, 0
	s_ashr_i32 s80, s74, 31
	v_lshl_or_b32 v152, s1, 6, v149
	v_lshl_or_b32 v149, s30, 7, v151
	s_waitcnt vmcnt(6)
	v_or_b32_e32 v148, s30, v148
	s_add_u32 s30, s2, s74
	s_addc_u32 s31, s31, s80
	s_add_i32 s82, 0, 0x10000
	s_add_i32 s83, 0, 0x14000
	s_sext_i32_i16 s88, s0
	s_mov_b32 s81, s74
	v_mov_b64_e32 v[136:137], 0x200
	v_mov_b64_e32 v[138:139], 0x1ff
	v_add_u32_e32 v150, s82, v149
	v_add_u32_e32 v151, s83, v149
	v_add_u32_e32 v153, 0, v0
	s_mov_b32 s84, 0x38b8ad1e
	s_mov_b64 s[34:35], 0x480000
	s_mov_b32 s85, 0x480000
	s_mov_b64 s[44:45], 0x500000
	s_mov_b32 s86, 0x500000
	s_mov_b64 s[46:47], 0x580000
	s_mov_b32 s87, 0x580000
	s_barrier
	s_branch .LBB0_251

; #define PG8_STAGE(bufoff, gbase, voff) do { _Pragma("unroll") for (int _i = 0; _i < 2; ++_i) \
;         __builtin_amdgcn_global_load_lds((const unsigned*)((const char*)(gbase) + (voff)[_i]), (PG8_LAS unsigned*)(lds + (bufoff) + ldsw + _i * 8192), 16, 0, 0); } while (0)
; #define PG8_WAIT_V(n) asm volatile("s_waitcnt vmcnt(" #n ")" ::: "memory")
; #define PG8_BAR __builtin_amdgcn_s_barrier()
; template <class Epi, class Sched, bool ALIGN_EPI = false, bool SP2 = false>
; __device__ __forceinline__ void gemm_phase(PG8_LAS unsigned char* lds, const Gemm g, const Sched& S, const Epi& E) {
;     ...
;         PG8_STAGE(PG8_SB(0, 0), cB, voffB); PG8_STAGE(PG8_SB(0, 1), cB + hstep, voffB); PG8_STAGE(PG8_SA(0, 0), cA, voffA); PG8_STAGE(PG8_SA(0, 1), cA + hstep, voffA);
;         if (wr == 1) PG8_BAR;
;         PG8_WAIT_V(2); PG8_BAR;
;         PG8_STAGE(PG8_SB(1, 0), cB + kstep, voffB); PG8_STAGE(PG8_SA(1, 0), cA + kstep, voffA); PG8_STAGE(PG8_SB(1, 1), cB + hstep + kstep, voffB);
;         PG8_WAIT_V(6); PG8_BAR;
.LBB0_470:
	s_mov_b64 s[20:21], 0x80
	s_and_b32 s56, s1, 3
	s_add_i32 m0, s33, 0x18000
	v_lshl_add_u64 v[6:7], v[6:7], 0, s[20:21]
	s_lshl_b32 s1, s0, 13
	s_lshl_b32 s11, s56, 12
	global_load_lds_dwordx4 v[6:7], off
	v_lshl_add_u64 v[4:5], v[4:5], 0, s[20:21]
	s_add_i32 m0, s33, 0x1a000
	s_add_i32 s57, s33, 0x8000
	s_add_i32 s58, s33, 0xa000
	global_load_lds_dwordx4 v[4:5], off
	v_lshl_add_u64 v[0:1], v[0:1], 0, s[98:99]
	s_mov_b32 m0, s57
	s_add_u32 s4, s6, 0x40080
	global_load_lds_dwordx4 v[0:1], off
	v_lshl_add_u64 v[0:1], v[2:3], 0, s[98:99]
	s_mov_b32 m0, s58
	s_addc_u32 s5, s7, 0
	global_load_lds_dwordx4 v[0:1], off
	s_add_i32 m0, s33, 0x1c000
	v_lshl_add_u64 v[0:1], s[4:5], 0, v[194:195]
	global_load_lds_dwordx4 v[0:1], off
	v_lshl_add_u64 v[0:1], s[4:5], 0, v[198:199]
	s_add_i32 m0, s33, 0x1e000
	v_lshlrev_b32_e32 v4, 2, v221
	global_load_lds_dwordx4 v[0:1], off
	s_waitcnt vmcnt(8)
	s_barrier
	v_bfe_u32 v1, v221, 4, 2
	v_and_b32_e32 v0, 15, v221
	v_lshlrev_b32_e32 v3, 4, v1
	v_lshl_or_b32 v222, s0, 6, v0
	v_lshl_or_b32 v0, v0, 6, v3
	v_and_b32_e32 v4, 32, v4
	v_lshlrev_b32_e32 v5, 6, v221
	s_movk_i32 s0, 0x3c0
	v_lshlrev_b32_e32 v2, 3, v1
	v_bitop3_b32 v0, v0, s1, v4 bitop3:0xde
	v_and_or_b32 v3, v5, s0, v3
	v_cmp_eq_u32_e64 s[0:1], 0, v1
	v_lshlrev_b32_e32 v1, 8, v221
	v_lshl_or_b32 v224, s56, 5, v2
	v_and_b32_e32 v1, 0x38000, v1
	v_lshlrev_b32_e32 v2, 11, v10
	s_cmpk_lt_u32 s10, 0x100
	v_or3_b32 v1, v8, v1, v2
	s_cselect_b64 s[26:27], -1, 0
	s_ashr_i32 s59, s74, 31
	s_ashr_i32 s61, s2, 31
	v_mov_b32_e32 v200, v252
	v_lshlrev_b32_e32 v1, 4, v11
	s_waitcnt vmcnt(6)
	s_cmp_lg_u64 s[18:19], 0
	v_and_b32_e32 v1, 0x78000, v1
	v_bitop3_b32 v223, s11, v3, v4 bitop3:0xf6
	s_cselect_b64 s[30:31], -1, 0
	v_or3_b32 v1, v8, v1, v2
	s_add_i32 s62, 0, 0x10000
	s_add_i32 s63, 0, 0x14000
	v_add_u32_e32 v227, 0, v0
	v_mbcnt_lo_u32_b32 v0, -1, 0
	s_mov_b32 s60, s74
	v_mov_b32_e32 v201, v195
	v_mov_b32_e32 v202, v253
	v_mov_b32_e32 v203, v195
	v_mov_b64_e32 v[204:205], 0x200
	v_mov_b64_e32 v[206:207], 0x1ff
	v_add_u32_e32 v225, s62, v223
	v_add_u32_e32 v226, s63, v223
	v_mbcnt_hi_u32_b32 v228, -1, v0
	s_mov_b32 s64, 0
	s_barrier
	s_branch .LBB0_473

; #define PG8_STAGE(bufoff, gbase, voff) do { _Pragma("unroll") for (int _i = 0; _i < 2; ++_i) \
;         __builtin_amdgcn_global_load_lds((const unsigned*)((const char*)(gbase) + (voff)[_i]), (PG8_LAS unsigned*)(lds + (bufoff) + ldsw + _i * 8192), 16, 0, 0); } while (0)
; #define PG8_WAIT_V(n) asm volatile("s_waitcnt vmcnt(" #n ")" ::: "memory")
; #define PG8_BAR __builtin_amdgcn_s_barrier()
; template <class Epi, class Sched, bool ALIGN_EPI = false, bool SP2 = false>
; __device__ __forceinline__ void gemm_phase(PG8_LAS unsigned char* lds, const Gemm g, const Sched& S, const Epi& E) {
;     ...
;         PG8_STAGE(PG8_SB(0, 0), cB, voffB); PG8_STAGE(PG8_SB(0, 1), cB + hstep, voffB); PG8_STAGE(PG8_SA(0, 0), cA, voffA); PG8_STAGE(PG8_SA(0, 1), cA + hstep, voffA);
;         if (wr == 1) PG8_BAR;
;         PG8_WAIT_V(2); PG8_BAR;
;         PG8_STAGE(PG8_SB(1, 0), cB + kstep, voffB); PG8_STAGE(PG8_SA(1, 0), cA + kstep, voffA); PG8_STAGE(PG8_SB(1, 1), cB + hstep + kstep, voffB);
;         PG8_WAIT_V(6); PG8_BAR;
.LBB0_569:
	s_lshl_b32 s12, s12, 5
	s_and_b32 s18, s12, 0x60
	s_mov_b64 s[12:13], 0x80
	s_add_i32 m0, s29, 0x18000
	v_lshl_add_u64 v[6:7], v[6:7], 0, s[12:13]
	s_lshl_b32 s15, s14, 13
	s_lshl_b32 s19, s18, 7
	global_load_lds_dwordx4 v[6:7], off
	v_lshl_add_u64 v[4:5], v[4:5], 0, s[12:13]
	s_add_i32 m0, s29, 0x1a000
	s_add_i32 s49, s29, 0x8000
	s_add_i32 s50, s29, 0xa000
	global_load_lds_dwordx4 v[4:5], off
	v_lshl_add_u64 v[0:1], v[0:1], 0, s[12:13]
	s_mov_b32 m0, s49
	s_add_u32 s16, s6, 0x40080
	global_load_lds_dwordx4 v[0:1], off
	v_lshl_add_u64 v[0:1], v[2:3], 0, s[12:13]
	s_mov_b32 m0, s50
	s_addc_u32 s17, s7, 0
	global_load_lds_dwordx4 v[0:1], off
	s_add_i32 m0, s29, 0x1c000
	v_lshl_add_u64 v[0:1], s[16:17], 0, v[132:133]
	global_load_lds_dwordx4 v[0:1], off
	v_lshl_add_u64 v[0:1], s[16:17], 0, v[128:129]
	s_add_i32 m0, s29, 0x1e000
	s_sext_i32_i16 s56, s0
	global_load_lds_dwordx4 v[0:1], off
	s_waitcnt vmcnt(8)
	s_barrier
	v_and_b32_e32 v0, 15, v221
	v_lshlrev_b32_e32 v1, 1, v11
	v_lshlrev_b32_e32 v2, 2, v221
	v_lshlrev_b32_e32 v3, 6, v221
	s_movk_i32 s0, 0x3c0
	v_lshl_or_b32 v146, s14, 6, v0
	v_lshl_or_b32 v0, v0, 6, v1
	v_and_b32_e32 v2, 32, v2
	v_and_or_b32 v1, v3, s0, v1
	v_bitop3_b32 v147, s19, v1, v2 bitop3:0xf6
	v_lshlrev_b32_e32 v1, 8, v221
	v_bitop3_b32 v0, v0, s15, v2 bitop3:0xde
	v_and_b32_e32 v1, 0x38000, v1
	v_lshlrev_b32_e32 v2, 11, v12
	v_or3_b32 v1, v9, v1, v2
	v_add_u32_e32 v136, v1, v10
	v_lshlrev_b32_e32 v1, 4, v8
	s_waitcnt vmcnt(6)
	s_cmpk_lt_u32 s1, 0x100
	v_and_b32_e32 v1, 0x78000, v1
	s_cselect_b64 s[14:15], -1, 0
	v_or3_b32 v1, v9, v1, v2
	s_add_i32 s53, 0, 0x10000
	s_add_i32 s54, 0, 0x14000
	s_ashr_i32 s51, s74, 31
	s_mov_b32 s52, s74
	v_or_b32_e32 v148, s18, v11
	v_mov_b32_e32 v137, v133
	v_add_u32_e32 v138, v1, v10
	v_mov_b32_e32 v139, v133
	v_mov_b64_e32 v[140:141], 0xb00
	v_mov_b64_e32 v[142:143], 0xaff
	v_add_u32_e32 v149, s53, v147
	v_add_u32_e32 v150, s54, v147
	v_add_u32_e32 v151, 0, v0
	v_mov_b32_e32 v152, 0x358637bd
	s_movk_i32 s55, 0x1600
	s_barrier
	s_branch .LBB0_572

; #define PG8_STAGE(bufoff, gbase, voff) do { _Pragma("unroll") for (int _i = 0; _i < 2; ++_i) \
;         __builtin_amdgcn_global_load_lds((const unsigned*)((const char*)(gbase) + (voff)[_i]), (PG8_LAS unsigned*)(lds + (bufoff) + ldsw + _i * 8192), 16, 0, 0); } while (0)
; #define PG8_WAIT_V(n) asm volatile("s_waitcnt vmcnt(" #n ")" ::: "memory")
; #define PG8_BAR __builtin_amdgcn_s_barrier()
; template <class Epi, class Sched, bool ALIGN_EPI = false, bool SP2 = false>
; __device__ __forceinline__ void gemm_phase(PG8_LAS unsigned char* lds, const Gemm g, const Sched& S, const Epi& E) {
;     ...
;         PG8_STAGE(PG8_SB(0, 0), cB, voffB); PG8_STAGE(PG8_SB(0, 1), cB + hstep, voffB); PG8_STAGE(PG8_SA(0, 0), cA, voffA); PG8_STAGE(PG8_SA(0, 1), cA + hstep, voffA);
;         if (wr == 1) PG8_BAR;
;         PG8_WAIT_V(2); PG8_BAR;
;         PG8_STAGE(PG8_SB(1, 0), cB + kstep, voffB); PG8_STAGE(PG8_SA(1, 0), cA + kstep, voffA); PG8_STAGE(PG8_SB(1, 1), cB + hstep + kstep, voffB);
;         PG8_WAIT_V(6); PG8_BAR;
.LBB0_646:
	s_mov_b64 s[18:19], 0x80
	s_and_b32 s37, s1, 3
	s_add_i32 m0, s33, 0x18000
	v_lshl_add_u64 v[6:7], v[6:7], 0, s[18:19]
	s_lshl_b32 s1, s0, 13
	s_lshl_b32 s9, s37, 12
	global_load_lds_dwordx4 v[6:7], off
	v_lshl_add_u64 v[4:5], v[4:5], 0, s[18:19]
	s_add_i32 m0, s33, 0x1a000
	s_add_i32 s46, s33, 0x8000
	s_add_i32 s47, s33, 0xa000
	global_load_lds_dwordx4 v[4:5], off
	v_lshl_add_u64 v[0:1], v[0:1], 0, s[18:19]
	s_mov_b32 m0, s46
	s_add_u32 s4, s6, 0xb0080
	global_load_lds_dwordx4 v[0:1], off
	v_lshl_add_u64 v[0:1], v[2:3], 0, s[18:19]
	s_mov_b32 m0, s47
	s_addc_u32 s5, s7, 0
	global_load_lds_dwordx4 v[0:1], off
	s_add_i32 m0, s33, 0x1c000
	v_lshl_add_u64 v[0:1], s[4:5], 0, v[154:155]
	global_load_lds_dwordx4 v[0:1], off
	v_lshl_add_u64 v[0:1], s[4:5], 0, v[158:159]
	s_add_i32 m0, s33, 0x1e000
	v_lshlrev_b32_e32 v4, 2, v221
	global_load_lds_dwordx4 v[0:1], off
	s_waitcnt vmcnt(8)
	s_barrier
	v_bfe_u32 v0, v221, 4, 2
	v_and_b32_e32 v1, 15, v221
	v_lshlrev_b32_e32 v3, 4, v0
	v_lshl_or_b32 v186, s0, 6, v1
	v_lshl_or_b32 v1, v1, 6, v3
	v_and_b32_e32 v4, 32, v4
	v_lshlrev_b32_e32 v5, 6, v221
	s_movk_i32 s0, 0x3c0
	v_lshlrev_b32_e32 v2, 3, v0
	v_bitop3_b32 v1, v1, s1, v4 bitop3:0xde
	v_and_or_b32 v3, v5, s0, v3
	v_cmp_eq_u32_e64 s[0:1], 0, v0
	v_add_u16_e32 v0, v8, v9
	s_waitcnt vmcnt(6)
	s_cmpk_lt_u32 s8, 0x100
	v_lshrrev_b16_e32 v0, 1, v0
	v_bitop3_b32 v187, s9, v3, v4 bitop3:0xf6
	s_cselect_b64 s[20:21], -1, 0
	v_add_lshl_u32 v160, v10, v0, 1
	v_add_lshl_u32 v162, v11, v0, 1
	s_add_i32 s51, 0, 0x10000
	s_add_i32 s52, 0, 0x14000
	v_mbcnt_lo_u32_b32 v0, -1, 0
	v_lshl_or_b32 v188, s37, 5, v2
	s_ashr_i32 s48, s74, 31
	s_mov_b32 s49, s74
	s_ashr_i32 s50, s2, 31
	v_mov_b32_e32 v161, v155
	v_mov_b32_e32 v163, v155
	v_mov_b64_e32 v[164:165], 0x200
	v_mov_b64_e32 v[166:167], 0x1ff
	v_add_u32_e32 v189, s51, v187
	v_add_u32_e32 v190, s52, v187
	v_add_u32_e32 v191, 0, v1
	v_mbcnt_hi_u32_b32 v192, -1, v0
	s_mov_b32 s53, 0
	s_barrier
	s_branch .LBB0_649

; __device__ __forceinline__ u32x4v pack8(const f32x4& a, const f32x4& b) { u32x4v w; w.x = cvt_pk_bf16(a[0], a[1]); w.y = cvt_pk_bf16(a[2], a[3]); w.z = cvt_pk_bf16(b[0], b[1]); w.w = cvt_pk_bf16(b[2], b[3]); return w; }
; #define PG8_STAGE(bufoff, gbase, voff) do { _Pragma("unroll") for (int _i = 0; _i < 2; ++_i) \
;         __builtin_amdgcn_global_load_lds((const unsigned*)((const char*)(gbase) + (voff)[_i]), (PG8_LAS unsigned*)(lds + (bufoff) + ldsw + _i * 8192), 16, 0, 0); } while (0)
; #define PG8_WAIT_V(n) asm volatile("s_waitcnt vmcnt(" #n ")" ::: "memory")
; #define PG8_BAR __builtin_amdgcn_s_barrier()
;     __device__ __forceinline__ void operator()(const f32x4 (&acc)[2][2][4][2], const Unit& u, int wr, int wc, int fr, int fq) const {
;     ...
;             for (int m = 0; m < 4; ++m) { const int r = row0 + ai * HALF + m * 16; const float rs = rstd[r]; bf16_t* rowp = O + (size_t)r * ldc + col0;
; #pragma unroll
;                 for (int bj = 0; bj < 2; ++bj) { const f32x4 v0 = acc[ai][bj][m][0] * rs + bv[bj][0], v1 = acc[ai][bj][m][1] * rs + bv[bj][1];
;                     const int c = col0 + bj * HALF;
;                     (void)rowp; *(u32x4v*)(O + (((size_t)(c >> 6) * 2 + ((c >> 5) & 1)) * 32768 + r) * 32 + (c & 31)) = pack8(v0, v1); } }
; template <class Epi, class Sched, bool ALIGN_EPI = false, bool SP2 = false>
; __device__ __forceinline__ void gemm_phase(PG8_LAS unsigned char* lds, const Gemm g, const Sched& S, const Epi& E) {
;     ...
;         PG8_STAGE(PG8_SB(0, 0), cB, voffB); PG8_STAGE(PG8_SB(0, 1), cB + hstep, voffB); PG8_STAGE(PG8_SA(0, 0), cA, voffA); PG8_STAGE(PG8_SA(0, 1), cA + hstep, voffA);
;         if (wr == 1) PG8_BAR;
;         PG8_WAIT_V(2); PG8_BAR;
;         PG8_STAGE(PG8_SB(1, 0), cB + kstep, voffB); PG8_STAGE(PG8_SA(1, 0), cA + kstep, voffA); PG8_STAGE(PG8_SB(1, 1), cB + hstep + kstep, voffB);
;         PG8_WAIT_V(6); PG8_BAR;
.LBB0_804:
	s_mov_b64 s[16:17], 0x80
	s_and_b32 s19, s1, 3
	s_add_i32 m0, s46, 0x18000
	v_lshl_add_u64 v[6:7], v[6:7], 0, s[16:17]
	s_lshl_b32 s26, s18, 13
	s_lshl_b32 s50, s19, 5
	global_load_lds_dwordx4 v[6:7], off
	v_lshl_add_u64 v[4:5], v[4:5], 0, s[16:17]
	s_add_i32 m0, s46, 0x1a000
	s_add_i32 s51, s46, 0x8000
	s_add_i32 s52, s46, 0xa000
	global_load_lds_dwordx4 v[4:5], off
	v_lshl_add_u64 v[0:1], v[0:1], 0, s[16:17]
	s_mov_b32 m0, s51
	s_add_u32 s20, s6, 0x40080
	global_load_lds_dwordx4 v[0:1], off
	v_lshl_add_u64 v[0:1], v[2:3], 0, s[16:17]
	s_mov_b32 m0, s52
	s_addc_u32 s21, s7, 0
	global_load_lds_dwordx4 v[0:1], off
	s_add_i32 m0, s46, 0x1c000
	v_lshl_add_u64 v[0:1], s[20:21], 0, v[148:149]
	global_load_lds_dwordx4 v[0:1], off
	v_lshl_add_u64 v[0:1], s[20:21], 0, v[152:153]
	s_add_i32 m0, s46, 0x1e000
	v_lshlrev_b32_e32 v2, 11, v170
	global_load_lds_dwordx4 v[0:1], off
	s_waitcnt vmcnt(8)
	s_barrier
	v_lshlrev_b32_e32 v1, 2, v145
	v_lshl_or_b32 v0, v145, 6, v172
	v_and_b32_e32 v1, 32, v1
	v_bitop3_b32 v0, v0, s26, v1 bitop3:0xde
	v_lshlrev_b32_e32 v1, 8, v221
	v_and_b32_e32 v1, 0x38000, v1
	v_or3_b32 v1, v168, v1, v2
	v_add_u32_e32 v156, v1, v169
	v_lshlrev_b32_e32 v1, 4, v171
	s_waitcnt vmcnt(6)
	s_cmpk_lt_u32 s12, 0x100
	v_and_b32_e32 v1, 0x78000, v1
	s_sext_i32_i8 s35, s0
	v_lshl_or_b32 v174, s18, 6, v145
	v_lshl_or_b32 v175, s19, 12, v173
	s_cselect_b64 s[18:19], -1, 0
	s_lshl_b32 s0, s1, 15
	v_or3_b32 v1, v168, v1, v2
	s_add_i32 s55, 0, 0x10000
	s_add_i32 s56, 0, 0x14000
	s_and_b32 s12, s0, 0x8000
	s_ashr_i32 s53, s74, 31
	s_mov_b32 s54, s74
	v_mov_b32_e32 v157, v155
	v_add_u32_e32 v158, v1, v169
	v_mov_b32_e32 v159, v155
	v_mov_b64_e32 v[160:161], 0x400
	v_mov_b64_e32 v[162:163], 0x3ff
	v_add_u32_e32 v176, s55, v175
	v_add_u32_e32 v177, s56, v175
	v_add_u32_e32 v178, 0, v0
	v_lshlrev_b32_e32 v154, 1, v144
	v_lshlrev_b32_e32 v154, 7, v144
	v_bfe_u32 v254, v145, 2, 1
	v_lshl_or_b32 v154, v254, 9, v154
	v_lshrrev_b32_e32 v254, 3, v145
	v_lshl_or_b32 v154, v254, 6, v154
	v_and_b32_e32 v254, 3, v145
	v_lshl_or_b32 v154, v254, 4, v154
	v_lshlrev_b32_e32 v254, 6, v145
	v_sub_u32_e32 v154, v154, v254
	v_ashrrev_i32_e32 v155, 31, v154
	s_mov_b32 s57, s13
	s_barrier
	s_branch .LBB0_807

; #define PG8_STAGE(bufoff, gbase, voff) do { _Pragma("unroll") for (int _i = 0; _i < 2; ++_i) \
;         __builtin_amdgcn_global_load_lds((const unsigned*)((const char*)(gbase) + (voff)[_i]), (PG8_LAS unsigned*)(lds + (bufoff) + ldsw + _i * 8192), 16, 0, 0); } while (0)
; #define PG8_WAIT_V(n) asm volatile("s_waitcnt vmcnt(" #n ")" ::: "memory")
; #define PG8_BAR __builtin_amdgcn_s_barrier()
; template <class Epi, class Sched, bool ALIGN_EPI = false, bool SP2 = false>
; __device__ __forceinline__ void gemm_phase(PG8_LAS unsigned char* lds, const Gemm g, const Sched& S, const Epi& E) {
;     ...
;         PG8_STAGE(PG8_SB(0, 0), cB, voffB); PG8_STAGE(PG8_SB(0, 1), cB + hstep, voffB); PG8_STAGE(PG8_SA(0, 0), cA, voffA); PG8_STAGE(PG8_SA(0, 1), cA + hstep, voffA);
;         if (wr == 1) PG8_BAR;
;         PG8_WAIT_V(2); PG8_BAR;
;         PG8_STAGE(PG8_SB(1, 0), cB + kstep, voffB); PG8_STAGE(PG8_SA(1, 0), cA + kstep, voffA); PG8_STAGE(PG8_SB(1, 1), cB + hstep + kstep, voffB);
;         PG8_WAIT_V(6); PG8_BAR;
.LBB0_828:
	s_add_u32 s12, s22, 0x2000
	s_addc_u32 s13, s23, 0
	s_lshl_b32 s1, s1, 5
	s_lshl_b32 s51, s14, 6
	s_lshl_b32 s17, s14, 13
	s_and_b32 s52, s1, 0x60
	s_add_u32 s53, s70, 0x14000000
	s_mov_b64 s[14:15], 0x80
	s_addc_u32 s54, s71, 0
	s_add_i32 m0, s46, 0x18000
	v_lshl_add_u64 v[6:7], v[6:7], 0, s[14:15]
	global_load_lds_dwordx4 v[6:7], off
	v_lshl_add_u64 v[4:5], v[4:5], 0, s[14:15]
	s_add_i32 m0, s46, 0x1a000
	s_add_i32 s55, s46, 0x8000
	s_add_i32 s56, s46, 0xa000
	global_load_lds_dwordx4 v[4:5], off
	v_lshl_add_u64 v[0:1], v[0:1], 0, s[14:15]
	s_mov_b32 m0, s55
	s_add_u32 s18, s6, 0x40080
	global_load_lds_dwordx4 v[0:1], off
	v_lshl_add_u64 v[0:1], v[2:3], 0, s[14:15]
	s_mov_b32 m0, s56
	s_addc_u32 s19, s7, 0
	global_load_lds_dwordx4 v[0:1], off
	s_add_i32 m0, s46, 0x1c000
	v_lshl_add_u64 v[0:1], s[18:19], 0, v[148:149]
	global_load_lds_dwordx4 v[0:1], off
	v_lshl_add_u64 v[0:1], s[18:19], 0, v[152:153]
	s_add_i32 m0, s46, 0x1e000
	v_lshlrev_b32_e32 v2, 8, v221
	global_load_lds_dwordx4 v[0:1], off
	s_waitcnt vmcnt(8)
	s_barrier
	v_and_b32_e32 v2, 0x38000, v2
	v_lshlrev_b32_e32 v3, 11, v170
	v_or3_b32 v2, v168, v2, v3
	v_lshlrev_b32_e32 v1, 2, v145
	v_add_u32_e32 v156, v2, v169
	v_lshlrev_b32_e32 v2, 4, v171
	v_lshl_or_b32 v0, v145, 6, v172
	v_and_b32_e32 v1, 32, v1
	s_waitcnt vmcnt(6)
	s_cmpk_lt_u32 s16, 0x100
	v_and_b32_e32 v2, 0x78000, v2
	v_bitop3_b32 v1, v0, s17, v1 bitop3:0xde
	v_lshl_or_b32 v172, s52, 7, v173
	s_cselect_b64 s[16:17], -1, 0
	v_lshlrev_b32_e32 v0, 3, v145
	v_or3_b32 v2, v168, v2, v3
	s_add_i32 s59, 0, 0x10000
	s_add_i32 s60, 0, 0x14000
	s_sext_i32_i16 s29, s0
	s_ashr_i32 s57, s74, 31
	s_mov_b32 s58, s74
	v_mov_b32_e32 v157, v155
	v_add_u32_e32 v158, v2, v169
	v_mov_b32_e32 v159, v155
	v_mov_b64_e32 v[160:161], 0x200
	v_mov_b64_e32 v[162:163], 0x1ff
	v_add_u32_e32 v170, s59, v172
	v_add_u32_e32 v171, s60, v172
	v_add_u32_e32 v173, 0, v1
	v_lshlrev_b32_e32 v164, 1, v0
	s_barrier
	s_branch .LBB0_831

; #define PG8_STAGE(bufoff, gbase, voff) do { _Pragma("unroll") for (int _i = 0; _i < 2; ++_i) \
;         __builtin_amdgcn_global_load_lds((const unsigned*)((const char*)(gbase) + (voff)[_i]), (PG8_LAS unsigned*)(lds + (bufoff) + ldsw + _i * 8192), 16, 0, 0); } while (0)
; #define PG8_WAIT_V(n) asm volatile("s_waitcnt vmcnt(" #n ")" ::: "memory")
; #define PG8_BAR __builtin_amdgcn_s_barrier()
; template <class Epi, class Sched, bool ALIGN_EPI = false, bool SP2 = false>
; __device__ __forceinline__ void gemm_phase(PG8_LAS unsigned char* lds, const Gemm g, const Sched& S, const Epi& E) {
;     ...
;         PG8_STAGE(PG8_SB(0, 0), cB, voffB); PG8_STAGE(PG8_SB(0, 1), cB + hstep, voffB); PG8_STAGE(PG8_SA(0, 0), cA, voffA); PG8_STAGE(PG8_SA(0, 1), cA + hstep, voffA);
;         if (wr == 1) PG8_BAR;
;         PG8_WAIT_V(2); PG8_BAR;
;         PG8_STAGE(PG8_SB(1, 0), cB + kstep, voffB); PG8_STAGE(PG8_SA(1, 0), cA + kstep, voffA); PG8_STAGE(PG8_SB(1, 1), cB + hstep + kstep, voffB);
;         PG8_WAIT_V(6); PG8_BAR;
.LBB0_977:
	s_mov_b64 s[16:17], 0x80
	s_and_b32 s46, s1, 3
	s_add_i32 m0, s31, 0x18000
	v_lshl_add_u64 v[6:7], v[6:7], 0, s[16:17]
	s_lshl_b32 s1, s0, 13
	s_lshl_b32 s19, s46, 12
	global_load_lds_dwordx4 v[6:7], off
	v_lshl_add_u64 v[4:5], v[4:5], 0, s[16:17]
	s_add_i32 m0, s31, 0x1a000
	s_add_i32 s47, s31, 0x8000
	s_add_i32 s48, s31, 0xa000
	global_load_lds_dwordx4 v[4:5], off
	v_lshl_add_u64 v[0:1], v[0:1], 0, s[16:17]
	s_mov_b32 m0, s47
	s_add_u32 s4, s6, 0x40080
	global_load_lds_dwordx4 v[0:1], off
	v_lshl_add_u64 v[0:1], v[2:3], 0, s[16:17]
	s_mov_b32 m0, s48
	s_addc_u32 s5, s7, 0
	global_load_lds_dwordx4 v[0:1], off
	s_add_i32 m0, s31, 0x1c000
	v_lshl_add_u64 v[0:1], s[4:5], 0, v[170:171]
	global_load_lds_dwordx4 v[0:1], off
	v_lshl_add_u64 v[0:1], s[4:5], 0, v[174:175]
	s_add_i32 m0, s31, 0x1e000
	v_lshlrev_b32_e32 v4, 2, v221
	global_load_lds_dwordx4 v[0:1], off
	s_waitcnt vmcnt(8)
	s_barrier
	v_bfe_u32 v0, v221, 4, 2
	v_and_b32_e32 v1, 15, v221
	v_lshlrev_b32_e32 v3, 4, v0
	v_lshl_or_b32 v202, s0, 6, v1
	v_lshl_or_b32 v1, v1, 6, v3
	v_and_b32_e32 v4, 32, v4
	v_lshlrev_b32_e32 v5, 6, v221
	s_movk_i32 s0, 0x3c0
	v_lshlrev_b32_e32 v2, 3, v0
	v_bitop3_b32 v1, v1, s1, v4 bitop3:0xde
	v_and_or_b32 v3, v5, s0, v3
	v_cmp_eq_u32_e64 s[0:1], 0, v0
	v_lshlrev_b32_e32 v0, 8, v221
	v_lshl_or_b32 v204, s46, 5, v2
	v_and_b32_e32 v0, 0x38000, v0
	v_lshlrev_b32_e32 v2, 11, v10
	v_or3_b32 v0, v8, v0, v2
	s_cmpk_lt_u32 s18, 0x100
	v_readlane_b32 s20, v248, 0
	v_add_u32_e32 v176, v0, v9
	v_lshlrev_b32_e32 v0, 4, v11
	v_bitop3_b32 v203, s19, v3, v4 bitop3:0xf6
	s_cselect_b64 s[18:19], -1, 0
	s_ashr_i32 s49, s74, 31
	s_ashr_i32 s51, s2, 31
	v_readlane_b32 s21, v248, 1
	v_and_b32_e32 v0, 0x78000, v0
	s_waitcnt vmcnt(6)
	s_cmp_lg_u64 s[20:21], 0
	v_or3_b32 v0, v8, v0, v2
	s_cselect_b64 s[20:21], -1, 0
	v_add_u32_e32 v178, v0, v9
	s_add_i32 s52, 0, 0x10000
	s_add_i32 s53, 0, 0x14000
	v_mbcnt_lo_u32_b32 v0, -1, 0
	s_mov_b32 s50, s74
	v_readlane_b32 s22, v248, 2
	v_readlane_b32 s24, v248, 4
	v_mov_b32_e32 v177, v171
	v_mov_b32_e32 v179, v171
	v_mov_b64_e32 v[180:181], 0x200
	v_mov_b64_e32 v[182:183], 0x1ff
	v_add_u32_e32 v205, s52, v203
	v_add_u32_e32 v206, s53, v203
	v_add_u32_e32 v207, 0, v1
	v_mbcnt_hi_u32_b32 v208, -1, v0
	s_mov_b32 s54, 0
	s_barrier
	v_readlane_b32 s23, v248, 3
	v_readlane_b32 s25, v248, 5
	v_readlane_b32 s26, v248, 6
	v_readlane_b32 s27, v248, 7
	s_branch .LBB0_980

; #define PG8_STAGE(bufoff, gbase, voff) do { _Pragma("unroll") for (int _i = 0; _i < 2; ++_i) \
;         __builtin_amdgcn_global_load_lds((const unsigned*)((const char*)(gbase) + (voff)[_i]), (PG8_LAS unsigned*)(lds + (bufoff) + ldsw + _i * 8192), 16, 0, 0); } while (0)
; #define PG8_WAIT_V(n) asm volatile("s_waitcnt vmcnt(" #n ")" ::: "memory")
; #define PG8_BAR __builtin_amdgcn_s_barrier()
; template <class Epi, class Sched, bool ALIGN_EPI = false, bool SP2 = false>
; __device__ __forceinline__ void gemm_phase(PG8_LAS unsigned char* lds, const Gemm g, const Sched& S, const Epi& E) {
;     ...
;         PG8_STAGE(PG8_SB(0, 0), cB, voffB); PG8_STAGE(PG8_SB(0, 1), cB + hstep, voffB); PG8_STAGE(PG8_SA(0, 0), cA, voffA); PG8_STAGE(PG8_SA(0, 1), cA + hstep, voffA);
;         if (wr == 1) PG8_BAR;
;         PG8_WAIT_V(2); PG8_BAR;
;         PG8_STAGE(PG8_SB(1, 0), cB + kstep, voffB); PG8_STAGE(PG8_SA(1, 0), cA + kstep, voffA); PG8_STAGE(PG8_SB(1, 1), cB + hstep + kstep, voffB);
;         PG8_WAIT_V(6); PG8_BAR;
.LBB0_1076:
	s_lshl_b32 s10, s10, 5
	s_and_b32 s16, s10, 0x60
	s_mov_b64 s[10:11], 0x80
	s_add_i32 m0, s23, 0x18000
	v_lshl_add_u64 v[6:7], v[6:7], 0, s[10:11]
	s_lshl_b32 s13, s12, 13
	s_lshl_b32 s17, s16, 7
	global_load_lds_dwordx4 v[6:7], off
	v_lshl_add_u64 v[4:5], v[4:5], 0, s[10:11]
	s_add_i32 m0, s23, 0x1a000
	s_add_i32 s37, s23, 0x8000
	s_add_i32 s44, s23, 0xa000
	global_load_lds_dwordx4 v[4:5], off
	v_lshl_add_u64 v[0:1], v[0:1], 0, s[10:11]
	s_mov_b32 m0, s37
	s_add_u32 s14, s6, 0x40080
	global_load_lds_dwordx4 v[0:1], off
	v_lshl_add_u64 v[0:1], v[2:3], 0, s[10:11]
	s_mov_b32 m0, s44
	s_addc_u32 s15, s7, 0
	global_load_lds_dwordx4 v[0:1], off
	s_add_i32 m0, s23, 0x1c000
	v_lshl_add_u64 v[0:1], s[14:15], 0, v[132:133]
	global_load_lds_dwordx4 v[0:1], off
	v_lshl_add_u64 v[0:1], s[14:15], 0, v[128:129]
	s_add_i32 m0, s23, 0x1e000
	s_sext_i32_i16 s50, s0
	global_load_lds_dwordx4 v[0:1], off
	s_waitcnt vmcnt(8)
	s_barrier
	v_and_b32_e32 v0, 15, v221
	v_lshlrev_b32_e32 v1, 1, v11
	v_lshlrev_b32_e32 v2, 2, v221
	v_lshlrev_b32_e32 v3, 6, v221
	s_movk_i32 s0, 0x3c0
	v_lshl_or_b32 v146, s12, 6, v0
	v_lshl_or_b32 v0, v0, 6, v1
	v_and_b32_e32 v2, 32, v2
	v_and_or_b32 v1, v3, s0, v1
	v_bitop3_b32 v147, s17, v1, v2 bitop3:0xf6
	v_lshlrev_b32_e32 v1, 8, v221
	v_bitop3_b32 v0, v0, s13, v2 bitop3:0xde
	v_and_b32_e32 v1, 0x38000, v1
	v_lshlrev_b32_e32 v2, 11, v12
	v_or3_b32 v1, v9, v1, v2
	v_add_u32_e32 v136, v1, v10
	v_lshlrev_b32_e32 v1, 4, v8
	s_waitcnt vmcnt(6)
	s_cmpk_lt_u32 s1, 0x100
	v_and_b32_e32 v1, 0x78000, v1
	s_cselect_b64 s[12:13], -1, 0
	v_or3_b32 v1, v9, v1, v2
	s_add_i32 s47, 0, 0x10000
	s_add_i32 s48, 0, 0x14000
	s_ashr_i32 s45, s74, 31
	s_mov_b32 s46, s74
	v_or_b32_e32 v148, s16, v11
	v_mov_b32_e32 v137, v133
	v_add_u32_e32 v138, v1, v10
	v_mov_b32_e32 v139, v133
	v_mov_b64_e32 v[140:141], 0xb00
	v_mov_b64_e32 v[142:143], 0xaff
	v_add_u32_e32 v149, s47, v147
	v_add_u32_e32 v150, s48, v147
	v_add_u32_e32 v151, 0, v0
	v_mov_b32_e32 v152, 0x358637bd
	s_movk_i32 s49, 0x1600
	s_barrier
	s_branch .LBB0_1079

; #define PG8_STAGE(bufoff, gbase, voff) do { _Pragma("unroll") for (int _i = 0; _i < 2; ++_i) \
;         __builtin_amdgcn_global_load_lds((const unsigned*)((const char*)(gbase) + (voff)[_i]), (PG8_LAS unsigned*)(lds + (bufoff) + ldsw + _i * 8192), 16, 0, 0); } while (0)
; #define PG8_WAIT_V(n) asm volatile("s_waitcnt vmcnt(" #n ")" ::: "memory")
; #define PG8_BAR __builtin_amdgcn_s_barrier()
; template <class Epi, class Sched, bool ALIGN_EPI = false, bool SP2 = false>
; __device__ __forceinline__ void gemm_phase(PG8_LAS unsigned char* lds, const Gemm g, const Sched& S, const Epi& E) {
;     ...
;         PG8_STAGE(PG8_SB(0, 0), cB, voffB); PG8_STAGE(PG8_SB(0, 1), cB + hstep, voffB); PG8_STAGE(PG8_SA(0, 0), cA, voffA); PG8_STAGE(PG8_SA(0, 1), cA + hstep, voffA);
;         if (wr == 1) PG8_BAR;
;         PG8_WAIT_V(2); PG8_BAR;
;         PG8_STAGE(PG8_SB(1, 0), cB + kstep, voffB); PG8_STAGE(PG8_SA(1, 0), cA + kstep, voffA); PG8_STAGE(PG8_SB(1, 1), cB + hstep + kstep, voffB);
;         PG8_WAIT_V(6); PG8_BAR;
.LBB0_1153:
	s_mov_b64 s[16:17], 0x80
	s_and_b32 s33, s1, 3
	s_add_i32 m0, s28, 0x18000
	v_lshl_add_u64 v[6:7], v[6:7], 0, s[16:17]
	s_lshl_b32 s1, s0, 13
	s_lshl_b32 s9, s33, 12
	global_load_lds_dwordx4 v[6:7], off
	v_lshl_add_u64 v[4:5], v[4:5], 0, s[16:17]
	s_add_i32 m0, s28, 0x1a000
	s_add_i32 s34, s28, 0x8000
	s_add_i32 s35, s28, 0xa000
	global_load_lds_dwordx4 v[4:5], off
	v_lshl_add_u64 v[0:1], v[0:1], 0, s[16:17]
	s_mov_b32 m0, s34
	s_add_u32 s4, s6, 0xb0080
	global_load_lds_dwordx4 v[0:1], off
	v_lshl_add_u64 v[0:1], v[2:3], 0, s[16:17]
	s_mov_b32 m0, s35
	s_addc_u32 s5, s7, 0
	global_load_lds_dwordx4 v[0:1], off
	s_add_i32 m0, s28, 0x1c000
	v_lshl_add_u64 v[0:1], s[4:5], 0, v[154:155]
	global_load_lds_dwordx4 v[0:1], off
	v_lshl_add_u64 v[0:1], s[4:5], 0, v[158:159]
	s_add_i32 m0, s28, 0x1e000
	v_lshlrev_b32_e32 v4, 2, v221
	global_load_lds_dwordx4 v[0:1], off
	s_waitcnt vmcnt(8)
	s_barrier
	v_bfe_u32 v0, v221, 4, 2
	v_and_b32_e32 v1, 15, v221
	v_lshlrev_b32_e32 v3, 4, v0
	v_lshl_or_b32 v186, s0, 6, v1
	v_lshl_or_b32 v1, v1, 6, v3
	v_and_b32_e32 v4, 32, v4
	v_lshlrev_b32_e32 v5, 6, v221
	s_movk_i32 s0, 0x3c0
	v_lshlrev_b32_e32 v2, 3, v0
	v_bitop3_b32 v1, v1, s1, v4 bitop3:0xde
	v_and_or_b32 v3, v5, s0, v3
	v_cmp_eq_u32_e64 s[0:1], 0, v0
	v_add_u16_e32 v0, v8, v9
	s_waitcnt vmcnt(6)
	s_cmpk_lt_u32 s8, 0x100
	v_lshrrev_b16_e32 v0, 1, v0
	v_bitop3_b32 v187, s9, v3, v4 bitop3:0xf6
	s_cselect_b64 s[18:19], -1, 0
	v_add_lshl_u32 v160, v10, v0, 1
	v_add_lshl_u32 v162, v11, v0, 1
	s_add_i32 s45, 0, 0x10000
	s_add_i32 s46, 0, 0x14000
	v_mbcnt_lo_u32_b32 v0, -1, 0
	v_lshl_or_b32 v188, s33, 5, v2
	s_ashr_i32 s36, s74, 31
	s_mov_b32 s37, s74
	s_ashr_i32 s44, s2, 31
	v_mov_b32_e32 v161, v155
	v_mov_b32_e32 v163, v155
	v_mov_b64_e32 v[164:165], 0x200
	v_mov_b64_e32 v[166:167], 0x1ff
	v_add_u32_e32 v189, s45, v187
	v_add_u32_e32 v190, s46, v187
	v_add_u32_e32 v191, 0, v1
	v_mbcnt_hi_u32_b32 v192, -1, v0
	s_mov_b32 s47, 0
	s_barrier
	s_branch .LBB0_1156
